# GEMM_IN row statistics prefetched before the K-loop (on top of UP prefetch)
# baseline (speedup 1.0000x reference)
; #define LAS __attribute__((address_space(3)))
; #define G_STAGE(bufoff, gbase, voff) do { const char* _gb = (const char*)(gbase); asm volatile("" : "+s"(_gb)); _Pragma("unroll") for (int _i = 0; _i < 2; ++_i) \
;         __builtin_amdgcn_global_load_lds((const unsigned*)(_gb + (voff)[_i]), (LAS unsigned*)(lds + (bufoff) + ldsw + _i * 8192), 16, 0, 0); } while (0)
; #define G_WAIT_V(n) asm volatile("s_waitcnt vmcnt(" #n ")" ::: "memory")
; #define G_BAR __builtin_amdgcn_s_barrier()
; template <class Epi>
; __device__ __forceinline__ void gemm_phase(LAS unsigned char* lds, const bf16_t* Ag, const bf16_t* Btg, const int K, const Sched& S, const Epi& E, int wv) {
;     ...
;     Unit cur, nxt; int ui = 0;
;     if (!S.next(0, cur)) return;
;     f32x4 acc[2][2][4][2];
; #pragma unroll
;     for (int a = 0; a < 2; ++a)
; #pragma unroll
;         for (int b = 0; b < 2; ++b)
; #pragma unroll
;             for (int m = 0; m < 4; ++m)
; #pragma unroll
;                 for (int n = 0; n < 2; ++n) acc[a][b][m][n] = (f32x4){0.f, 0.f, 0.f, 0.f};
;     bf16x8 At[4][2], B0[2][2], B1[2][2];
;     const char* cA = (const char*)Ag + cur.arow * (long)rowb;
;     const char* cB0 = (const char*)Btg + (size_t)cur.b0 * rowb;
;     const char* cB1 = (const char*)Btg + (size_t)cur.b1 * rowb;
;     G_STAGE(G_SB(0, 0), cB0, voffB); G_STAGE(G_SA(0, 0), cA, voffA); G_STAGE(G_SB(0, 1), cB1, voffB); G_STAGE(G_SA(0, 1), cA + hstep, voffA);
;     if (wr == 1) G_BAR;
;     G_WAIT_V(4); G_BAR;
;     G_STAGE(G_SB(1, 0), cB0 + kstep, voffB); G_STAGE(G_SA(1, 0), cA + kstep, voffA); G_STAGE(G_SB(1, 1), cB1 + kstep, voffB);
;     G_WAIT_V(6); G_BAR;
;     for (;;) {
;         const bool has_next = S.next(ui + 1, nxt);
;         const char* nA = has_next ? (const char*)Ag + nxt.arow * (long)rowb : cA;
;         const char* nB0 = has_next ? (const char*)Btg + (size_t)nxt.b0 * rowb : cB0;
;         const char* nB1 = has_next ? (const char*)Btg + (size_t)nxt.b1 * rowb : cB1;
; __device__ __forceinline__ void stage_rstd(LAS unsigned char* lds, const float* ss, int tid, long grow0, int sr0, int L) {
;     if (tid < 256) {
;         const int sr = sr0 + tid; const bool valid = sr >= 0 && sr < L;
;         const f32x4* q = (const f32x4*)(ss + (size_t)(valid ? grow0 + tid : 0) * 16);
;         const f32x4 a = q[0], b = q[1], c = q[2], d = q[3];
.LBB0_917:
	v_mov_b64_e32 v[2:3], 0x6c0
	v_cmp_lt_i64_e32 vcc, s[14:15], v[2:3]
	s_lshl_b64 s[14:15], s[12:13], 11
	s_add_u32 s14, s4, s14
	s_addc_u32 s15, s5, s15
	s_and_b64 s[16:17], vcc, exec
	s_cselect_b32 s7, s15, s43
	s_cselect_b32 s37, s14, s42
	s_ashr_i32 s9, s8, 31
	s_lshl_b64 s[16:17], s[8:9], 11
	v_readlane_b32 s48, v254, 26
	v_readlane_b32 s49, v254, 27
	s_add_u32 s16, s48, s16
	s_addc_u32 s17, s49, s17
	s_and_b64 s[18:19], vcc, exec
	s_cselect_b32 s9, s17, s45
	s_cselect_b32 s39, s16, s44
	s_ashr_i32 s11, s10, 31
	s_lshl_b64 s[18:19], s[10:11], 11
	s_add_u32 s18, s48, s18
	s_addc_u32 s19, s49, s19
	s_and_b64 s[48:49], vcc, exec
	s_cselect_b32 s11, s19, s47
	s_cselect_b32 s41, s18, s46
	s_add_u32 s67, s44, 0x100
	s_addc_u32 s68, s45, 0
	s_add_u32 s69, s46, 0x100
	v_mov_b32_e32 v2, 0
	s_addc_u32 s70, s47, 0
	s_mov_b32 s71, -2
	v_mov_b32_e32 v3, v2
	v_mov_b32_e32 v4, v2
	v_mov_b32_e32 v5, v2
	v_mov_b32_e32 v6, v2
	v_mov_b32_e32 v7, v2
	v_mov_b32_e32 v8, v2
	v_mov_b32_e32 v9, v2
	v_mov_b32_e32 v18, v2
	v_mov_b32_e32 v19, v2
	v_mov_b32_e32 v20, v2
	v_mov_b32_e32 v21, v2
	v_mov_b32_e32 v22, v2
	v_mov_b32_e32 v23, v2
	v_mov_b32_e32 v24, v2
	v_mov_b32_e32 v25, v2
	v_mov_b32_e32 v34, v2
	v_mov_b32_e32 v35, v2
	v_mov_b32_e32 v36, v2
	v_mov_b32_e32 v37, v2
	v_mov_b32_e32 v38, v2
	v_mov_b32_e32 v39, v2
	v_mov_b32_e32 v40, v2
	v_mov_b32_e32 v41, v2
	v_mov_b32_e32 v50, v2
	v_mov_b32_e32 v51, v2
	v_mov_b32_e32 v52, v2
	v_mov_b32_e32 v53, v2
	v_mov_b32_e32 v54, v2
	v_mov_b32_e32 v55, v2
	v_mov_b32_e32 v56, v2
	v_mov_b32_e32 v57, v2
	v_mov_b32_e32 v10, v2
	v_mov_b32_e32 v11, v2
	v_mov_b32_e32 v12, v2
	v_mov_b32_e32 v13, v2
	v_mov_b32_e32 v14, v2
	v_mov_b32_e32 v15, v2
	v_mov_b32_e32 v16, v2
	v_mov_b32_e32 v17, v2
	v_mov_b32_e32 v26, v2
	v_mov_b32_e32 v27, v2
	v_mov_b32_e32 v28, v2
	v_mov_b32_e32 v29, v2
	v_mov_b32_e32 v30, v2
	v_mov_b32_e32 v31, v2
	v_mov_b32_e32 v32, v2
	v_mov_b32_e32 v33, v2
	v_mov_b32_e32 v42, v2
	v_mov_b32_e32 v43, v2
	v_mov_b32_e32 v44, v2
	v_mov_b32_e32 v45, v2
	v_mov_b32_e32 v46, v2
	v_mov_b32_e32 v47, v2
	v_mov_b32_e32 v48, v2
	v_mov_b32_e32 v49, v2
	v_mov_b32_e32 v58, v2
	v_mov_b32_e32 v59, v2
	v_mov_b32_e32 v60, v2
	v_mov_b32_e32 v61, v2
	v_mov_b32_e32 v62, v2
	v_mov_b32_e32 v63, v2
	v_mov_b32_e32 v64, v2
	v_mov_b32_e32 v65, v2
	v_mov_b32_e32 v66, v2
	v_mov_b32_e32 v67, v2
	v_mov_b32_e32 v68, v2
	v_mov_b32_e32 v69, v2
	v_mov_b32_e32 v70, v2
	v_mov_b32_e32 v71, v2
	v_mov_b32_e32 v72, v2
	v_mov_b32_e32 v73, v2
	v_mov_b32_e32 v82, v2
	v_mov_b32_e32 v83, v2
	v_mov_b32_e32 v84, v2
	v_mov_b32_e32 v85, v2
	v_mov_b32_e32 v86, v2
	v_mov_b32_e32 v87, v2
	v_mov_b32_e32 v88, v2
	v_mov_b32_e32 v89, v2
	v_mov_b32_e32 v98, v2
	v_mov_b32_e32 v99, v2
	v_mov_b32_e32 v100, v2
	v_mov_b32_e32 v101, v2
	v_mov_b32_e32 v102, v2
	v_mov_b32_e32 v103, v2
	v_mov_b32_e32 v104, v2
	v_mov_b32_e32 v105, v2
	v_mov_b32_e32 v114, v2
	v_mov_b32_e32 v115, v2
	v_mov_b32_e32 v116, v2
	v_mov_b32_e32 v117, v2
	v_mov_b32_e32 v118, v2
	v_mov_b32_e32 v119, v2
	v_mov_b32_e32 v120, v2
	v_mov_b32_e32 v121, v2
	v_mov_b32_e32 v74, v2
	v_mov_b32_e32 v75, v2
	v_mov_b32_e32 v76, v2
	v_mov_b32_e32 v77, v2
	v_mov_b32_e32 v78, v2
	v_mov_b32_e32 v79, v2
	v_mov_b32_e32 v80, v2
	v_mov_b32_e32 v81, v2
	v_mov_b32_e32 v90, v2
	v_mov_b32_e32 v91, v2
	v_mov_b32_e32 v92, v2
	v_mov_b32_e32 v93, v2
	v_mov_b32_e32 v94, v2
	v_mov_b32_e32 v95, v2
	v_mov_b32_e32 v96, v2
	v_mov_b32_e32 v97, v2
	v_mov_b32_e32 v106, v2
	v_mov_b32_e32 v107, v2
	v_mov_b32_e32 v108, v2
	v_mov_b32_e32 v109, v2
	v_mov_b32_e32 v110, v2
	v_mov_b32_e32 v111, v2
	v_mov_b32_e32 v112, v2
	v_mov_b32_e32 v113, v2
	v_mov_b32_e32 v122, v2
	v_mov_b32_e32 v123, v2
	v_mov_b32_e32 v124, v2
	v_mov_b32_e32 v125, v2
	v_mov_b32_e32 v126, v2
	v_mov_b32_e32 v127, v2
	v_mov_b32_e32 v128, v2
	v_mov_b32_e32 v129, v2
	s_cmp_lg_u32 s55, 0
	s_cbranch_scc1 .Lmy_in_pf_done
	v_lshlrev_b32_e32 v196, 4, v139
	v_add_u32_e32 v196, v196, v138
	v_lshl_add_u32 v196, s62, 6, v196
	v_lshlrev_b32_e32 v196, 6, v196
	v_mov_b32_e32 v197, 0
	s_lshl_b32 s32, s40, 14
	s_add_u32 s98, s2, s32
	s_addc_u32 s99, s3, 0
	v_lshl_add_u64 v[196:197], s[98:99], 0, v[196:197]
	global_load_dwordx4 v[206:209], v[196:197], off offset:48
	global_load_dwordx4 v[210:213], v[196:197], off offset:32
	global_load_dwordx4 v[198:201], v[196:197], off offset:16
	global_load_dwordx4 v[226:229], v[196:197], off
; #define G_STAGE(bufoff, gbase, voff) do { const char* _gb = (const char*)(gbase); asm volatile("" : "+s"(_gb)); _Pragma("unroll") for (int _i = 0; _i < 2; ++_i) \
;         __builtin_amdgcn_global_load_lds((const unsigned*)(_gb + (voff)[_i]), (LAS unsigned*)(lds + (bufoff) + ldsw + _i * 8192), 16, 0, 0); } while (0)
; #define G_LDA(dst, b, h) do { _Pragma("unroll") for (int m = 0; m < 4; ++m) _Pragma("unroll") for (int k = 0; k < 2; ++k) dst[m][k] = *(const LAS bf16x8*)(lds + G_SA(b, h) + aoff + m * 2048 + k * 1024); } while (0)
; #define G_LDB(dst, b, h) do { _Pragma("unroll") for (int n = 0; n < 2; ++n) _Pragma("unroll") for (int k = 0; k < 2; ++k) dst[n][k] = *(const LAS bf16x8*)(lds + G_SB(b, h) + boff + n * 2048 + k * 1024); } while (0)
; #define G_WAIT_L(n) asm volatile("s_waitcnt lgkmcnt(" #n ")" ::: "memory")
; #define G_BAR __builtin_amdgcn_s_barrier()
; #define G_SCHED __builtin_amdgcn_sched_barrier(0)
; template <class Epi>
; __device__ __forceinline__ void gemm_phase(LAS unsigned char* lds, const bf16_t* Ag, const bf16_t* Btg, const int K, const Sched& S, const Epi& E, int wv) {
;     ...
;         const bool has_next = S.next(ui + 1, nxt);
;         const char* nA = has_next ? (const char*)Ag + nxt.arow * (long)rowb : cA;
;         const char* nB0 = has_next ? (const char*)Btg + (size_t)nxt.b0 * rowb : cB0;
;         const char* nB1 = has_next ? (const char*)Btg + (size_t)nxt.b1 * rowb : cB1;
;         for (int t = 0; t < nt; t += 2) {
;             const bool last = (t == nt - 2);
;             const char* a1 = cA + (size_t)(t + 1) * kstep;
;             const char* a2 = last ? nA : cA + (size_t)(t + 2) * kstep;
;             const char* b20 = last ? nB0 : cB0 + (size_t)(t + 2) * kstep;
;             const char* b21 = last ? nB1 : cB1 + (size_t)(t + 2) * kstep;
;             const char* a3 = a2 + kstep; const char* b30 = b20 + kstep; const char* b31 = b21 + kstep;
;             G_LDB(B0, 0, 0); G_SCHED; G_LDA(At, 0, 0); G_STAGE(G_SA(1, 1), a1 + hstep, voffA);
;             G_WAIT_L(8); G_BAR; G_WAIT_L(0); G_MMA(0, 0, At, B0); G_BAR; G_SCHED;
;             G_LDB(B1, 0, 1); G_STAGE(G_SB(0, 0), b20, voffB);
;             G_BAR; G_WAIT_L(0); G_MMA(0, 1, At, B1); G_BAR;
;             G_LDA(At, 0, 1); G_STAGE(G_SA(0, 0), a2, voffA);
;             G_BAR; G_WAIT_L(0); G_MMA(1, 0, At, B0); G_BAR; G_SCHED;
.Lmy_in_pf_done:
.LBB0_918:
	s_add_u32 s44, s42, 0x100
	s_addc_u32 s45, s43, 0
	s_cmp_eq_u32 s71, 12
	s_cselect_b32 s72, s39, s67
	s_cselect_b32 s73, s9, s68
	s_cselect_b32 s47, s11, s70
	s_cselect_b32 s46, s41, s69
	s_cselect_b32 s52, s37, s44
	s_cselect_b32 s53, s7, s45
	s_add_u32 s50, s72, 0x80
	s_addc_u32 s51, s73, 0
	s_add_i32 s74, 0, 0x10000
	v_add_u32_e32 v0, s74, v140
	ds_read_b128 v[142:145], v0
	ds_read_b128 v[146:149], v0 offset:1024
	ds_read_b128 v[150:153], v0 offset:2048
	ds_read_b128 v[154:157], v0 offset:3072
	s_add_u32 s48, s52, 0x80
	s_addc_u32 s49, s53, 0
	s_add_u32 s42, s42, 0x40080
	s_addc_u32 s43, s43, 0
	ds_read_b128 v[158:161], v141
	ds_read_b128 v[162:165], v141 offset:1024
	ds_read_b128 v[166:169], v141 offset:2048
	ds_read_b128 v[170:173], v141 offset:3072
	ds_read_b128 v[174:177], v141 offset:4096
	ds_read_b128 v[178:181], v141 offset:5120
	ds_read_b128 v[182:185], v141 offset:6144
	ds_read_b128 v[186:189], v141 offset:7168
	s_add_i32 m0, s58, 0xc000
	v_lshl_add_u64 v[190:191], s[42:43], 0, v[136:137]
	global_load_lds_dwordx4 v[190:191], off
	v_lshl_add_u64 v[190:191], s[42:43], 0, v[132:133]
	s_add_i32 m0, s58, 0xe000
	s_nop 0
	global_load_lds_dwordx4 v[190:191], off
	s_waitcnt lgkmcnt(8)
	s_barrier
	s_waitcnt lgkmcnt(0)
	s_setprio 1
	s_waitcnt lgkmcnt(0)
	v_mfma_f32_16x16x32_bf16 v[126:129], v[142:145], v[158:161], v[126:129]
	v_mfma_f32_16x16x32_bf16 v[122:125], v[150:153], v[158:161], v[122:125]
	v_mfma_f32_16x16x32_bf16 v[110:113], v[142:145], v[166:169], v[110:113]
	v_mfma_f32_16x16x32_bf16 v[106:109], v[150:153], v[166:169], v[106:109]
	v_mfma_f32_16x16x32_bf16 v[94:97], v[142:145], v[174:177], v[94:97]
	v_mfma_f32_16x16x32_bf16 v[90:93], v[150:153], v[174:177], v[90:93]
	v_mfma_f32_16x16x32_bf16 v[78:81], v[142:145], v[182:185], v[78:81]
	v_mfma_f32_16x16x32_bf16 v[74:77], v[150:153], v[182:185], v[74:77]
	v_mfma_f32_16x16x32_bf16 v[126:129], v[146:149], v[162:165], v[126:129]
	v_mfma_f32_16x16x32_bf16 v[122:125], v[154:157], v[162:165], v[122:125]
	v_mfma_f32_16x16x32_bf16 v[110:113], v[146:149], v[170:173], v[110:113]
	v_mfma_f32_16x16x32_bf16 v[106:109], v[154:157], v[170:173], v[106:109]
	v_mfma_f32_16x16x32_bf16 v[94:97], v[146:149], v[178:181], v[94:97]
	v_mfma_f32_16x16x32_bf16 v[90:93], v[154:157], v[178:181], v[90:93]
	v_mfma_f32_16x16x32_bf16 v[78:81], v[146:149], v[186:189], v[78:81]
	v_mfma_f32_16x16x32_bf16 v[74:77], v[154:157], v[186:189], v[74:77]
	s_setprio 0
	s_barrier
	s_add_i32 s75, 0, 0x14000
	v_add_u32_e32 v0, s75, v140
	s_add_i32 s42, s74, s56
	ds_read_b128 v[190:193], v0
	ds_read_b128 v[214:217], v0 offset:1024
	ds_read_b128 v[218:221], v0 offset:2048
	ds_read_b128 v[222:225], v0 offset:3072
	s_mov_b32 m0, s42
	v_lshl_add_u64 v[194:195], s[72:73], 0, v[134:135]
	global_load_lds_dwordx4 v[194:195], off
	v_lshl_add_u64 v[194:195], s[72:73], 0, v[130:131]
	s_add_i32 m0, s42, 0x2000
	s_nop 0
	global_load_lds_dwordx4 v[194:195], off
	s_barrier
	s_waitcnt lgkmcnt(0)
	s_setprio 1
	s_waitcnt lgkmcnt(0)
	v_mfma_f32_16x16x32_bf16 v[118:121], v[190:193], v[158:161], v[118:121]
	v_mfma_f32_16x16x32_bf16 v[114:117], v[218:221], v[158:161], v[114:117]
	v_mfma_f32_16x16x32_bf16 v[102:105], v[190:193], v[166:169], v[102:105]
	v_mfma_f32_16x16x32_bf16 v[98:101], v[218:221], v[166:169], v[98:101]
	v_mfma_f32_16x16x32_bf16 v[86:89], v[190:193], v[174:177], v[86:89]
	v_mfma_f32_16x16x32_bf16 v[82:85], v[218:221], v[174:177], v[82:85]
	v_mfma_f32_16x16x32_bf16 v[70:73], v[190:193], v[182:185], v[70:73]
	v_mfma_f32_16x16x32_bf16 v[66:69], v[218:221], v[182:185], v[66:69]
	v_mfma_f32_16x16x32_bf16 v[118:121], v[214:217], v[162:165], v[118:121]
	v_mfma_f32_16x16x32_bf16 v[114:117], v[222:225], v[162:165], v[114:117]
	v_mfma_f32_16x16x32_bf16 v[102:105], v[214:217], v[170:173], v[102:105]
	v_mfma_f32_16x16x32_bf16 v[98:101], v[222:225], v[170:173], v[98:101]
	v_mfma_f32_16x16x32_bf16 v[86:89], v[214:217], v[178:181], v[86:89]
	v_mfma_f32_16x16x32_bf16 v[82:85], v[222:225], v[178:181], v[82:85]
	v_mfma_f32_16x16x32_bf16 v[70:73], v[214:217], v[186:189], v[70:73]
	v_mfma_f32_16x16x32_bf16 v[66:69], v[222:225], v[186:189], v[66:69]
	s_setprio 0
	s_mov_b64 s[42:43], s[52:53]
	s_mov_b32 m0, s58
	s_barrier
	ds_read_b128 v[158:161], v141 offset:16384
	ds_read_b128 v[162:165], v141 offset:17408
	ds_read_b128 v[166:169], v141 offset:18432
	ds_read_b128 v[170:173], v141 offset:19456
	ds_read_b128 v[174:177], v141 offset:20480
	ds_read_b128 v[178:181], v141 offset:21504
	ds_read_b128 v[182:185], v141 offset:22528
	ds_read_b128 v[186:189], v141 offset:23552
	s_nop 0
	v_lshl_add_u64 v[194:195], s[42:43], 0, v[136:137]
	global_load_lds_dwordx4 v[194:195], off
	v_lshl_add_u64 v[194:195], s[42:43], 0, v[132:133]
	s_mov_b32 m0, s59
	s_nop 0
	global_load_lds_dwordx4 v[194:195], off
	s_barrier
	s_waitcnt lgkmcnt(0)
	s_setprio 1
	s_waitcnt lgkmcnt(0)
	v_mfma_f32_16x16x32_bf16 v[62:65], v[142:145], v[158:161], v[62:65]
	v_mfma_f32_16x16x32_bf16 v[58:61], v[150:153], v[158:161], v[58:61]
	v_mfma_f32_16x16x32_bf16 v[46:49], v[142:145], v[166:169], v[46:49]
	v_mfma_f32_16x16x32_bf16 v[42:45], v[150:153], v[166:169], v[42:45]
	v_mfma_f32_16x16x32_bf16 v[30:33], v[142:145], v[174:177], v[30:33]
	v_mfma_f32_16x16x32_bf16 v[26:29], v[150:153], v[174:177], v[26:29]
	v_mfma_f32_16x16x32_bf16 v[14:17], v[142:145], v[182:185], v[14:17]
	v_mfma_f32_16x16x32_bf16 v[10:13], v[150:153], v[182:185], v[10:13]
	v_mfma_f32_16x16x32_bf16 v[62:65], v[146:149], v[162:165], v[62:65]
	v_mfma_f32_16x16x32_bf16 v[58:61], v[154:157], v[162:165], v[58:61]
	v_mfma_f32_16x16x32_bf16 v[46:49], v[146:149], v[170:173], v[46:49]
	v_mfma_f32_16x16x32_bf16 v[42:45], v[154:157], v[170:173], v[42:45]
	v_mfma_f32_16x16x32_bf16 v[30:33], v[146:149], v[178:181], v[30:33]
	v_mfma_f32_16x16x32_bf16 v[26:29], v[154:157], v[178:181], v[26:29]
	v_mfma_f32_16x16x32_bf16 v[14:17], v[146:149], v[186:189], v[14:17]
	v_mfma_f32_16x16x32_bf16 v[10:13], v[154:157], v[186:189], v[10:13]
	s_setprio 0
	s_barrier
; #define G_STAGE(bufoff, gbase, voff) do { const char* _gb = (const char*)(gbase); asm volatile("" : "+s"(_gb)); _Pragma("unroll") for (int _i = 0; _i < 2; ++_i) \
;         __builtin_amdgcn_global_load_lds((const unsigned*)(_gb + (voff)[_i]), (LAS unsigned*)(lds + (bufoff) + ldsw + _i * 8192), 16, 0, 0); } while (0)
; #define G_LDA(dst, b, h) do { _Pragma("unroll") for (int m = 0; m < 4; ++m) _Pragma("unroll") for (int k = 0; k < 2; ++k) dst[m][k] = *(const LAS bf16x8*)(lds + G_SA(b, h) + aoff + m * 2048 + k * 1024); } while (0)
; #define G_LDB(dst, b, h) do { _Pragma("unroll") for (int n = 0; n < 2; ++n) _Pragma("unroll") for (int k = 0; k < 2; ++k) dst[n][k] = *(const LAS bf16x8*)(lds + G_SB(b, h) + boff + n * 2048 + k * 1024); } while (0)
; #define G_MMA(ai, bj, At, Bt) do { __builtin_amdgcn_s_setprio(1); _Pragma("unroll") for (int m = 0; m < 4; ++m) _Pragma("unroll") for (int n = 0; n < 2; ++n) _Pragma("unroll") for (int k = 0; k < 2; ++k) \
;         acc[ai][bj][m][n] = __builtin_amdgcn_mfma_f32_16x16x32_bf16(Bt[n][k], At[m][k], acc[ai][bj][m][n], 0, 0, 0); __builtin_amdgcn_s_setprio(0); } while (0)
; #define G_WAIT_V(n) asm volatile("s_waitcnt vmcnt(" #n ")" ::: "memory")
; #define G_WAIT_L(n) asm volatile("s_waitcnt lgkmcnt(" #n ")" ::: "memory")
; #define G_BAR __builtin_amdgcn_s_barrier()
; #define G_SCHED __builtin_amdgcn_sched_barrier(0)
; template <class Epi>
; __device__ __forceinline__ void gemm_phase(LAS unsigned char* lds, const bf16_t* Ag, const bf16_t* Btg, const int K, const Sched& S, const Epi& E, int wv) {
;     ...
;             G_STAGE(G_SB(0, 1), b21, voffB);
;             G_WAIT_V(6); G_BAR; G_MMA(1, 1, At, B1); G_BAR;
;             G_LDB(B0, 1, 0); G_SCHED; G_LDA(At, 1, 0); G_STAGE(G_SA(0, 1), a2 + hstep, voffA);
;             G_WAIT_L(8); G_BAR; G_WAIT_L(0); G_MMA(0, 0, At, B0); G_BAR; G_SCHED;
;             G_LDB(B1, 1, 1); G_STAGE(G_SB(1, 0), b30, voffB);
;             G_BAR; G_WAIT_L(0); G_MMA(0, 1, At, B1); G_BAR;
;             G_LDA(At, 1, 1); G_STAGE(G_SA(1, 0), a3, voffA);
;             G_BAR; G_WAIT_L(0); G_MMA(1, 0, At, B0); G_BAR; G_SCHED;
	s_mov_b64 s[42:43], s[46:47]
	s_add_i32 s72, s75, s56
	s_mov_b32 m0, s72
	v_lshl_add_u64 v[142:143], s[42:43], 0, v[134:135]
	global_load_lds_dwordx4 v[142:143], off
	v_lshl_add_u64 v[142:143], s[42:43], 0, v[130:131]
	s_add_i32 m0, s72, 0x2000
	s_nop 0
	global_load_lds_dwordx4 v[142:143], off
	s_waitcnt vmcnt(6)
	s_barrier
	s_setprio 1
	v_mfma_f32_16x16x32_bf16 v[54:57], v[190:193], v[158:161], v[54:57]
	v_mfma_f32_16x16x32_bf16 v[50:53], v[218:221], v[158:161], v[50:53]
	v_mfma_f32_16x16x32_bf16 v[38:41], v[190:193], v[166:169], v[38:41]
	v_mfma_f32_16x16x32_bf16 v[34:37], v[218:221], v[166:169], v[34:37]
	v_mfma_f32_16x16x32_bf16 v[22:25], v[190:193], v[174:177], v[22:25]
	v_mfma_f32_16x16x32_bf16 v[18:21], v[218:221], v[174:177], v[18:21]
	v_mfma_f32_16x16x32_bf16 v[6:9], v[190:193], v[182:185], v[6:9]
	v_mfma_f32_16x16x32_bf16 v[2:5], v[218:221], v[182:185], v[2:5]
	v_mfma_f32_16x16x32_bf16 v[54:57], v[214:217], v[162:165], v[54:57]
	v_mfma_f32_16x16x32_bf16 v[50:53], v[222:225], v[162:165], v[50:53]
	v_mfma_f32_16x16x32_bf16 v[38:41], v[214:217], v[170:173], v[38:41]
	v_mfma_f32_16x16x32_bf16 v[34:37], v[222:225], v[170:173], v[34:37]
	v_mfma_f32_16x16x32_bf16 v[22:25], v[214:217], v[178:181], v[22:25]
	v_mfma_f32_16x16x32_bf16 v[18:21], v[222:225], v[178:181], v[18:21]
	v_mfma_f32_16x16x32_bf16 v[6:9], v[214:217], v[186:189], v[6:9]
	v_mfma_f32_16x16x32_bf16 v[2:5], v[222:225], v[186:189], v[2:5]
	s_setprio 0
	s_add_i32 s72, 0, 0x18000
	v_add_u32_e32 v0, s72, v140
	s_barrier
	ds_read_b128 v[142:145], v0
	ds_read_b128 v[146:149], v0 offset:1024
	ds_read_b128 v[150:153], v0 offset:2048
	ds_read_b128 v[154:157], v0 offset:3072
	s_add_u32 s42, s52, 0x40000
	s_addc_u32 s43, s53, 0
	s_mov_b32 m0, s60
	ds_read_b128 v[158:161], v141 offset:32768
	ds_read_b128 v[162:165], v141 offset:33792
	ds_read_b128 v[166:169], v141 offset:34816
	ds_read_b128 v[170:173], v141 offset:35840
	ds_read_b128 v[174:177], v141 offset:36864
	ds_read_b128 v[178:181], v141 offset:37888
	ds_read_b128 v[182:185], v141 offset:38912
	ds_read_b128 v[186:189], v141 offset:39936
	s_nop 0
	v_lshl_add_u64 v[190:191], s[42:43], 0, v[136:137]
	global_load_lds_dwordx4 v[190:191], off
	v_lshl_add_u64 v[190:191], s[42:43], 0, v[132:133]
	s_mov_b32 m0, s61
	s_nop 0
	global_load_lds_dwordx4 v[190:191], off
	s_waitcnt lgkmcnt(8)
	s_barrier
	s_waitcnt lgkmcnt(0)
	s_setprio 1
	s_waitcnt lgkmcnt(0)
	v_mfma_f32_16x16x32_bf16 v[126:129], v[142:145], v[158:161], v[126:129]
	v_mfma_f32_16x16x32_bf16 v[122:125], v[150:153], v[158:161], v[122:125]
	v_mfma_f32_16x16x32_bf16 v[110:113], v[142:145], v[166:169], v[110:113]
	v_mfma_f32_16x16x32_bf16 v[106:109], v[150:153], v[166:169], v[106:109]
	v_mfma_f32_16x16x32_bf16 v[94:97], v[142:145], v[174:177], v[94:97]
	v_mfma_f32_16x16x32_bf16 v[90:93], v[150:153], v[174:177], v[90:93]
	v_mfma_f32_16x16x32_bf16 v[78:81], v[142:145], v[182:185], v[78:81]
	v_mfma_f32_16x16x32_bf16 v[74:77], v[150:153], v[182:185], v[74:77]
	v_mfma_f32_16x16x32_bf16 v[126:129], v[146:149], v[162:165], v[126:129]
	v_mfma_f32_16x16x32_bf16 v[122:125], v[154:157], v[162:165], v[122:125]
	v_mfma_f32_16x16x32_bf16 v[110:113], v[146:149], v[170:173], v[110:113]
	v_mfma_f32_16x16x32_bf16 v[106:109], v[154:157], v[170:173], v[106:109]
	v_mfma_f32_16x16x32_bf16 v[94:97], v[146:149], v[178:181], v[94:97]
	v_mfma_f32_16x16x32_bf16 v[90:93], v[154:157], v[178:181], v[90:93]
	v_mfma_f32_16x16x32_bf16 v[78:81], v[146:149], v[186:189], v[78:81]
	v_mfma_f32_16x16x32_bf16 v[74:77], v[154:157], v[186:189], v[74:77]
	s_setprio 0
	s_barrier
	s_add_i32 s52, 0, 0x1c000
	v_add_u32_e32 v0, s52, v140
	s_add_i32 s42, s72, s56
	ds_read_b128 v[190:193], v0
	ds_read_b128 v[214:217], v0 offset:1024
	ds_read_b128 v[218:221], v0 offset:2048
	ds_read_b128 v[222:225], v0 offset:3072
	s_mov_b32 m0, s42
	v_lshl_add_u64 v[194:195], s[50:51], 0, v[134:135]
	global_load_lds_dwordx4 v[194:195], off
	v_lshl_add_u64 v[194:195], s[50:51], 0, v[130:131]
	s_add_i32 m0, s42, 0x2000
	s_nop 0
	global_load_lds_dwordx4 v[194:195], off
	s_barrier
	s_waitcnt lgkmcnt(0)
	s_setprio 1
	s_waitcnt lgkmcnt(0)
	v_mfma_f32_16x16x32_bf16 v[118:121], v[190:193], v[158:161], v[118:121]
	v_mfma_f32_16x16x32_bf16 v[114:117], v[218:221], v[158:161], v[114:117]
	v_mfma_f32_16x16x32_bf16 v[102:105], v[190:193], v[166:169], v[102:105]
	v_mfma_f32_16x16x32_bf16 v[98:101], v[218:221], v[166:169], v[98:101]
	v_mfma_f32_16x16x32_bf16 v[86:89], v[190:193], v[174:177], v[86:89]
	v_mfma_f32_16x16x32_bf16 v[82:85], v[218:221], v[174:177], v[82:85]
	v_mfma_f32_16x16x32_bf16 v[70:73], v[190:193], v[182:185], v[70:73]
	v_mfma_f32_16x16x32_bf16 v[66:69], v[218:221], v[182:185], v[66:69]
	v_mfma_f32_16x16x32_bf16 v[118:121], v[214:217], v[162:165], v[118:121]
	v_mfma_f32_16x16x32_bf16 v[114:117], v[222:225], v[162:165], v[114:117]
	v_mfma_f32_16x16x32_bf16 v[102:105], v[214:217], v[170:173], v[102:105]
	v_mfma_f32_16x16x32_bf16 v[98:101], v[222:225], v[170:173], v[98:101]
	v_mfma_f32_16x16x32_bf16 v[86:89], v[214:217], v[178:181], v[86:89]
	v_mfma_f32_16x16x32_bf16 v[82:85], v[222:225], v[178:181], v[82:85]
	v_mfma_f32_16x16x32_bf16 v[70:73], v[214:217], v[186:189], v[70:73]
	v_mfma_f32_16x16x32_bf16 v[66:69], v[222:225], v[186:189], v[66:69]
	s_setprio 0
	s_mov_b32 m0, s63
	s_barrier
; #define LAS __attribute__((address_space(3)))
; #define G_STAGE(bufoff, gbase, voff) do { const char* _gb = (const char*)(gbase); asm volatile("" : "+s"(_gb)); _Pragma("unroll") for (int _i = 0; _i < 2; ++_i) \
;         __builtin_amdgcn_global_load_lds((const unsigned*)(_gb + (voff)[_i]), (LAS unsigned*)(lds + (bufoff) + ldsw + _i * 8192), 16, 0, 0); } while (0)
; #define G_MMA(ai, bj, At, Bt) do { __builtin_amdgcn_s_setprio(1); _Pragma("unroll") for (int m = 0; m < 4; ++m) _Pragma("unroll") for (int n = 0; n < 2; ++n) _Pragma("unroll") for (int k = 0; k < 2; ++k) \
;         acc[ai][bj][m][n] = __builtin_amdgcn_mfma_f32_16x16x32_bf16(Bt[n][k], At[m][k], acc[ai][bj][m][n], 0, 0, 0); __builtin_amdgcn_s_setprio(0); } while (0)
; #define G_WAIT_V(n) asm volatile("s_waitcnt vmcnt(" #n ")" ::: "memory")
; #define G_WAIT_L(n) asm volatile("s_waitcnt lgkmcnt(" #n ")" ::: "memory")
; #define G_BAR __builtin_amdgcn_s_barrier()
; #define G_SCHED __builtin_amdgcn_sched_barrier(0)
; template <class Epi>
; __device__ __forceinline__ void gemm_phase(LAS unsigned char* lds, const bf16_t* Ag, const bf16_t* Btg, const int K, const Sched& S, const Epi& E, int wv) {
;     ...
;             G_BAR; G_WAIT_L(0); G_MMA(1, 0, At, B0); G_BAR; G_SCHED;
;             G_STAGE(G_SB(1, 1), b31, voffB);
;             G_WAIT_V(6); G_BAR; G_MMA(1, 1, At, B1); G_BAR;
; __device__ __forceinline__ void stage_rstd(LAS unsigned char* lds, const float* ss, int tid, long grow0, int sr0, int L) {
;     if (tid < 256) {
;         const int sr = sr0 + tid; const bool valid = sr >= 0 && sr < L;
;         const f32x4* q = (const f32x4*)(ss + (size_t)(valid ? grow0 + tid : 0) * 16);
;         const f32x4 a = q[0], b = q[1], c = q[2], d = q[3];
;         const float sm_ = ((a.x + a.y) + (a.z + a.w)) + ((b.x + b.y) + (b.z + b.w)) + ((c.x + c.y) + (c.z + c.w)) + ((d.x + d.y) + (d.z + d.w));
;         ((LAS float*)(lds + EPI_RS))[tid] = valid ? rsqrtf(sm_ * (1.0f / 1024.0f) + EPS) : 0.f;
	ds_read_b128 v[158:161], v141 offset:49152
	ds_read_b128 v[162:165], v141 offset:50176
	ds_read_b128 v[166:169], v141 offset:51200
	ds_read_b128 v[170:173], v141 offset:52224
	ds_read_b128 v[174:177], v141 offset:53248
	ds_read_b128 v[178:181], v141 offset:54272
	ds_read_b128 v[182:185], v141 offset:55296
	ds_read_b128 v[186:189], v141 offset:56320
	s_nop 0
	v_lshl_add_u64 v[194:195], s[48:49], 0, v[136:137]
	global_load_lds_dwordx4 v[194:195], off
	v_lshl_add_u64 v[194:195], s[48:49], 0, v[132:133]
	s_mov_b32 m0, s64
	s_nop 0
	global_load_lds_dwordx4 v[194:195], off
	s_barrier
	s_waitcnt lgkmcnt(0)
	s_setprio 1
	s_waitcnt lgkmcnt(0)
	v_mfma_f32_16x16x32_bf16 v[62:65], v[142:145], v[158:161], v[62:65]
	s_add_u32 s42, s46, 0x80
	s_addc_u32 s43, s47, 0
	v_mfma_f32_16x16x32_bf16 v[58:61], v[150:153], v[158:161], v[58:61]
	v_mfma_f32_16x16x32_bf16 v[46:49], v[142:145], v[166:169], v[46:49]
	v_mfma_f32_16x16x32_bf16 v[42:45], v[150:153], v[166:169], v[42:45]
	v_mfma_f32_16x16x32_bf16 v[30:33], v[142:145], v[174:177], v[30:33]
	v_mfma_f32_16x16x32_bf16 v[26:29], v[150:153], v[174:177], v[26:29]
	v_mfma_f32_16x16x32_bf16 v[14:17], v[142:145], v[182:185], v[14:17]
	v_mfma_f32_16x16x32_bf16 v[10:13], v[150:153], v[182:185], v[10:13]
	v_mfma_f32_16x16x32_bf16 v[62:65], v[146:149], v[162:165], v[62:65]
	v_mfma_f32_16x16x32_bf16 v[58:61], v[154:157], v[162:165], v[58:61]
	v_mfma_f32_16x16x32_bf16 v[46:49], v[146:149], v[170:173], v[46:49]
	v_mfma_f32_16x16x32_bf16 v[42:45], v[154:157], v[170:173], v[42:45]
	v_mfma_f32_16x16x32_bf16 v[30:33], v[146:149], v[178:181], v[30:33]
	v_mfma_f32_16x16x32_bf16 v[26:29], v[154:157], v[178:181], v[26:29]
	v_mfma_f32_16x16x32_bf16 v[14:17], v[146:149], v[186:189], v[14:17]
	v_mfma_f32_16x16x32_bf16 v[10:13], v[154:157], v[186:189], v[10:13]
	s_setprio 0
	s_barrier
	s_add_i32 s46, s52, s56
	s_mov_b32 m0, s46
	v_lshl_add_u64 v[142:143], s[42:43], 0, v[134:135]
	global_load_lds_dwordx4 v[142:143], off
	v_lshl_add_u64 v[142:143], s[42:43], 0, v[130:131]
	s_add_i32 m0, s46, 0x2000
	s_nop 0
	global_load_lds_dwordx4 v[142:143], off
	s_waitcnt vmcnt(6)
	s_barrier
	s_setprio 1
	v_mfma_f32_16x16x32_bf16 v[54:57], v[190:193], v[158:161], v[54:57]
	v_mfma_f32_16x16x32_bf16 v[50:53], v[218:221], v[158:161], v[50:53]
	v_mfma_f32_16x16x32_bf16 v[38:41], v[190:193], v[166:169], v[38:41]
	v_mfma_f32_16x16x32_bf16 v[34:37], v[218:221], v[166:169], v[34:37]
	v_mfma_f32_16x16x32_bf16 v[22:25], v[190:193], v[174:177], v[22:25]
	v_mfma_f32_16x16x32_bf16 v[18:21], v[218:221], v[174:177], v[18:21]
	v_mfma_f32_16x16x32_bf16 v[6:9], v[190:193], v[182:185], v[6:9]
	v_mfma_f32_16x16x32_bf16 v[2:5], v[218:221], v[182:185], v[2:5]
	v_mfma_f32_16x16x32_bf16 v[54:57], v[214:217], v[162:165], v[54:57]
	v_mfma_f32_16x16x32_bf16 v[50:53], v[222:225], v[162:165], v[50:53]
	v_mfma_f32_16x16x32_bf16 v[38:41], v[214:217], v[170:173], v[38:41]
	v_mfma_f32_16x16x32_bf16 v[34:37], v[222:225], v[170:173], v[34:37]
	v_mfma_f32_16x16x32_bf16 v[22:25], v[214:217], v[178:181], v[22:25]
	v_mfma_f32_16x16x32_bf16 v[18:21], v[222:225], v[178:181], v[18:21]
	v_mfma_f32_16x16x32_bf16 v[6:9], v[214:217], v[186:189], v[6:9]
	v_mfma_f32_16x16x32_bf16 v[2:5], v[222:225], v[186:189], v[2:5]
	s_setprio 0
	s_add_i32 s71, s71, 2
	s_add_u32 s67, s67, 0x100
	s_addc_u32 s68, s68, 0
	s_add_u32 s69, s69, 0x100
	s_addc_u32 s70, s70, 0
	s_cmp_gt_u32 s71, 13
	s_mov_b64 s[42:43], s[44:45]
	s_barrier
	s_cbranch_scc0 .LBB0_918
	v_mov_b32_e32 v142, v139
	s_mov_b32 s9, s62
	v_mov_b32_e32 v143, v138
	s_mov_b32 s11, s55
	s_lshl_b32 s7, s11, 8
	s_lshl_b32 s37, s9, 6
	v_lshlrev_b32_e32 v0, 4, v142
	s_add_i32 s37, s7, s37
	v_add3_u32 v0, s37, v143, v0
	s_movk_i32 s37, 0x100
	v_cmp_gt_i32_e32 vcc, s37, v0
	s_and_saveexec_b64 s[42:43], vcc
	v_readlane_b32 s72, v254, 29
	s_mov_b64 s[68:69], 0x800
	v_readlane_b32 s73, v254, 30
	s_cbranch_execz .LBB0_914
	v_cmp_gt_u32_e32 vcc, 2.0, v0
	v_mov_b32_e32 v144, 0
	s_and_saveexec_b64 s[44:45], vcc
	s_cbranch_execz .LBB0_913
	s_ashr_i32 s41, s40, 31
	v_mov_b32_e32 v144, v206
	v_mov_b32_e32 v145, v207
	v_mov_b32_e32 v146, v208
	v_mov_b32_e32 v147, v209
	v_mov_b32_e32 v148, v210
	v_mov_b32_e32 v149, v211
	v_mov_b32_e32 v150, v212
	v_mov_b32_e32 v151, v213
	v_mov_b32_e32 v152, v198
	v_mov_b32_e32 v153, v199
	v_mov_b32_e32 v154, v200
	v_mov_b32_e32 v155, v201
	v_mov_b32_e32 v156, v226
	v_mov_b32_e32 v157, v227
	v_mov_b32_e32 v158, v228
	v_mov_b32_e32 v159, v229
	s_mov_b32 s37, 0x800000
	v_add_f32_e32 v148, v148, v149
	v_add_f32_e32 v150, v150, v151
	v_mov_b32_e32 v160, v157
	v_mov_b32_e32 v161, v158
	v_mov_b32_e32 v157, v159
	v_mov_b32_e32 v158, v153
	v_mov_b32_e32 v159, v154
	v_mov_b32_e32 v153, v155
	v_pk_add_f32 v[156:157], v[160:161], v[156:157]
	v_pk_add_f32 v[152:153], v[158:159], v[152:153]
	v_pk_add_f32 v[156:157], v[156:157], v[156:157] op_sel:[0,1] op_sel_hi:[1,0]
	v_pk_add_f32 v[152:153], v[152:153], v[152:153] op_sel:[0,1] op_sel_hi:[1,0]
	v_mov_b32_e32 v157, v144
	v_mov_b32_e32 v153, v145
	v_mov_b32_e32 v149, v146
	v_mov_b32_e32 v151, v147
	v_pk_add_f32 v[144:145], v[156:157], v[152:153]
	v_pk_add_f32 v[146:147], v[148:149], v[150:151]
	s_nop 0
	v_pk_add_f32 v[144:145], v[144:145], v[146:147]
	s_nop 0
	v_add_f32_e32 v144, v144, v145
	v_fmamk_f32 v144, v144, 0x3a800000, v205
	v_cmp_gt_f32_e32 vcc, s37, v144
	v_mul_f32_e32 v145, 0x4b800000, v144
	s_nop 0
	v_cndmask_b32_e32 v144, v144, v145, vcc
	v_rsq_f32_e32 v144, v144
	s_nop 0
	v_mul_f32_e32 v145, 0x45800000, v144
	v_cndmask_b32_e32 v144, v144, v145, vcc
	s_branch .LBB0_913
